# v46 + panel hand-offs (P3/P8/P11): no per-workgroup agent-scope L2 writeback before the panel count (producers and consumers of a panel share one XCD L2; the seam that follows still releases)
# speedup vs baseline: 1.0214x; 1.0214x over previous
.LBB0_348:
	s_waitcnt vmcnt(0)
	s_waitcnt vmcnt(0)
	s_barrier
	s_mov_b64 s[2:3], exec
	v_readlane_b32 s6, v246, 40
	v_readlane_b32 s7, v246, 41
	s_and_b64 s[6:7], s[2:3], s[6:7]
	s_mov_b64 exec, s[6:7]
	s_cbranch_execz .LBB0_372
	s_lshl_b32 s6, s14, 4
	s_mov_b64 s[8:9], exec
	s_ashr_i32 s7, s6, 31
	s_lshl_b64 s[6:7], s[6:7], 2
	v_readlane_b32 s10, v246, 44
	s_waitcnt vmcnt(0)
	v_mbcnt_lo_u32_b32 v0, s8, 0
	s_add_u32 s6, s10, s6
	v_readlane_b32 s10, v246, 45
	v_mbcnt_hi_u32_b32 v0, s9, v0
	s_addc_u32 s7, s10, s7
	v_cmp_eq_u32_e32 vcc, 0, v0
	s_and_saveexec_b64 s[10:11], vcc
	s_cbranch_execz .LBB0_351
	s_bcnt1_i32_b64 s8, s[8:9]
	v_mov_b32_e32 v0, 0
	v_mov_b32_e32 v1, s8
	global_atomic_add v0, v1, s[6:7]

.LBB0_1054:
	s_waitcnt vmcnt(0)
	s_waitcnt vmcnt(0)
	s_barrier
	s_mov_b64 s[2:3], exec
	v_readlane_b32 s4, v246, 40
	v_readlane_b32 s5, v246, 41
	s_and_b64 s[4:5], s[2:3], s[4:5]
	s_mov_b64 exec, s[4:5]
	s_cbranch_execz .LBB0_1078
	s_lshl_b32 s4, s14, 4
	s_addk_i32 s4, 0x500
	s_mov_b64 s[8:9], exec
	s_ashr_i32 s5, s4, 31
	s_lshl_b64 s[4:5], s[4:5], 2
	v_readlane_b32 s10, v246, 44
	s_waitcnt vmcnt(0)
	v_mbcnt_lo_u32_b32 v0, s8, 0
	s_add_u32 s4, s10, s4
	v_readlane_b32 s10, v246, 45
	v_mbcnt_hi_u32_b32 v0, s9, v0
	s_addc_u32 s5, s10, s5
	v_cmp_eq_u32_e32 vcc, 0, v0
	s_and_saveexec_b64 s[10:11], vcc
	s_cbranch_execz .LBB0_1057
	s_bcnt1_i32_b64 s8, s[8:9]
	v_mov_b32_e32 v0, 0
	v_mov_b32_e32 v1, s8
	global_atomic_add v0, v1, s[4:5]

.LBB0_1342:
	s_waitcnt vmcnt(0)
	s_waitcnt vmcnt(0)
	s_barrier
	s_mov_b64 s[2:3], exec
	v_readlane_b32 s4, v246, 40
	v_readlane_b32 s5, v246, 41
	s_and_b64 s[4:5], s[2:3], s[4:5]
	s_mov_b64 exec, s[4:5]
	s_cbranch_execz .LBB0_1366
	s_lshl_b32 s4, s14, 4
	s_addk_i32 s4, 0xa00
	s_mov_b64 s[6:7], exec
	s_ashr_i32 s5, s4, 31
	s_lshl_b64 s[4:5], s[4:5], 2
	v_readlane_b32 s10, v246, 44
	s_waitcnt vmcnt(0)
	v_mbcnt_lo_u32_b32 v0, s6, 0
	s_add_u32 s4, s10, s4
	v_readlane_b32 s10, v246, 45
	v_mbcnt_hi_u32_b32 v0, s7, v0
	s_addc_u32 s5, s10, s5
	v_cmp_eq_u32_e32 vcc, 0, v0
	s_and_saveexec_b64 s[10:11], vcc
	s_cbranch_execz .LBB0_1345
	s_bcnt1_i32_b64 s6, s[6:7]
	v_mov_b32_e32 v0, 0
	v_mov_b32_e32 v1, s6
	global_atomic_add v0, v1, s[4:5]
